# MLA loop: uniform K loads + vmcnt(3); GEMM epilogue: prefetch all 8 row-sum loads at once, drop per-row-block vmcnt(0) drains
# speedup vs baseline: 1.0095x; 1.0095x over previous
.LBB0_232:
	s_lshl_b32 s10, s14, 8
	v_readlane_b32 s11, v243, 43
	s_add_i32 s10, s10, s11
	v_add_u32_e32 v144, s10, v144
	v_mov_b32_e32 v146, 1.0
	s_andn2_b64 vcc, exec, s[8:9]
	v_ashrrev_i32_e32 v145, 31, v144
	s_cbranch_vccnz .LBB0_234
	v_readlane_b32 s6, v243, 58
	v_readlane_b32 s7, v243, 59
	s_nop 1
	v_lshl_add_u64 v[146:147], v[144:145], 3, s[6:7]
	global_load_dwordx2 v[214:215], v[146:147], off offset:128
	global_load_dwordx2 v[216:217], v[146:147], off offset:256
	global_load_dwordx2 v[218:219], v[146:147], off offset:384
	global_load_dwordx2 v[220:221], v[146:147], off offset:1024
	global_load_dwordx2 v[222:223], v[146:147], off offset:1152
	global_load_dwordx2 v[224:225], v[146:147], off offset:1280
	global_load_dwordx2 v[226:227], v[146:147], off offset:1408
	global_load_dwordx2 v[146:147], v[146:147], off
	s_mov_b64 s[6:7], 0
	s_waitcnt vmcnt(0)
	v_ffbh_u32_e32 v150, v147
	v_min_u32_e32 v150, 32, v150
	v_lshlrev_b64 v[146:147], v150, v[146:147]
	v_min_u32_e32 v146, 1, v146
	v_or_b32_e32 v146, v147, v146
	v_cvt_f32_u32_e32 v146, v146
	v_sub_u32_e32 v147, 32, v150
	v_ldexp_f32 v146, v146, v147
	v_fmaak_f32 v146, v192, v146, 0x358637bd
	v_rsq_f32_e32 v146, v146

.LBB0_362:
	s_andn2_b64 vcc, exec, s[50:51]
	v_readlane_b32 s50, v243, 58
	v_readlane_b32 s51, v243, 59
	v_mov_b32_e32 v118, 1.0
	s_waitcnt lgkmcnt(0)
	v_lshl_add_u64 v[114:115], v[144:145], 3, s[50:51]
	s_cbranch_vccnz .LBB0_364
	v_mov_b32_e32 v116, v214
	v_mov_b32_e32 v117, v215
	s_mov_b64 s[82:83], 0
	v_ffbh_u32_e32 v118, v117
	v_min_u32_e32 v118, 32, v118
	v_lshlrev_b64 v[116:117], v118, v[116:117]
	v_min_u32_e32 v116, 1, v116
	v_or_b32_e32 v116, v117, v116
	v_cvt_f32_u32_e32 v116, v116
	v_sub_u32_e32 v117, 32, v118
	v_ldexp_f32 v116, v116, v117
	v_fmaak_f32 v116, v192, v116, 0x358637bd
	v_rsq_f32_e32 v118, v116
.LBB0_364:
	v_add_u32_e32 v116, 16, v144
	s_andn2_b64 vcc, exec, s[82:83]
	v_ashrrev_i32_e32 v117, 31, v116
	s_cbranch_vccnz .LBB0_366
	v_lshl_add_u64 v[118:119], v[116:117], 2, s[66:67]
	global_load_dword v118, v[118:119], off
	s_waitcnt vmcnt(0)
.LBB0_366:
	v_mul_f32_e32 v119, 0x3e16c740, v118
	v_lshlrev_b64 v[120:121], 11, v[116:117]
	v_cndmask_b32_e64 v164, v118, v119, s[52:53]
	v_lshlrev_b64 v[118:119], 10, v[116:117]
	v_lshl_add_u64 v[160:161], s[88:89], 0, v[120:121]
	v_lshlrev_b64 v[124:125], 12, v[116:117]
	v_lshl_add_u64 v[158:159], s[34:35], 0, v[120:121]
	v_lshlrev_b64 v[120:121], 13, v[116:117]
	v_lshl_add_u64 v[168:169], v[148:149], 0, v[124:125]
	v_lshl_add_u64 v[152:153], s[2:3], 0, v[118:119]
	v_lshl_add_u64 v[170:171], s[28:29], 0, v[120:121]
	v_pk_mul_f32 v[162:163], v[112:113], v[164:165] op_sel_hi:[1,0]
	v_pk_mul_f32 v[174:175], v[110:111], v[164:165] op_sel_hi:[1,0]
	v_pk_mul_f32 v[176:177], v[108:109], v[164:165] op_sel_hi:[1,0]
	v_pk_mul_f32 v[178:179], v[106:107], v[164:165] op_sel_hi:[1,0]
	s_cmp_lt_i32 s62, 4
	s_mov_b64 s[50:51], -1
	s_cbranch_scc1 .LBB0_385
	s_cmp_lt_i32 s62, 6
	s_cbranch_scc1 .LBB0_376
	s_cmp_gt_i32 s62, 6
	s_cbranch_scc0 .LBB0_370
	v_max_f32_e32 v107, v178, v178
	v_max_f32_e32 v111, v176, v176
	v_max_f32_e32 v106, v174, v174
	v_max_f32_e32 v108, 0, v107
	v_max_f32_e32 v107, v175, v175
	v_max_f32_e32 v109, v179, v179
	v_max_f32_e32 v110, v162, v162
	v_max_f32_e32 v112, 0, v111
	v_max_f32_e32 v111, v163, v163
	v_max_f32_e32 v113, v177, v177
	v_max_f32_e32 v106, 0, v106
	v_max_f32_e32 v107, 0, v107
	v_max_f32_e32 v109, 0, v109
	v_max_f32_e32 v110, 0, v110
	v_max_f32_e32 v111, 0, v111
	v_max_f32_e32 v113, 0, v113
	v_pk_mul_f32 v[106:107], v[106:107], v[106:107]
	v_pk_mul_f32 v[108:109], v[108:109], v[108:109]
	v_pk_mul_f32 v[110:111], v[110:111], v[110:111]
	v_pk_mul_f32 v[112:113], v[112:113], v[112:113]
	v_ashrrev_i32_e32 v147, 31, v146
	v_lshl_add_u64 v[120:121], v[146:147], 1, v[170:171]
	v_cvt_pk_bf16_f32 v106, v106, v107
	v_cvt_pk_bf16_f32 v107, v110, v111
	v_cvt_pk_bf16_f32 v108, v108, v109
	v_cvt_pk_bf16_f32 v109, v112, v113
	global_store_dwordx4 v[120:121], v[106:109], off
	s_mov_b64 s[50:51], 0

.LBB0_492:
	v_lshl_add_u64 v[100:101], v[98:99], 2, s[66:67]
	global_load_dword v100, v[100:101], off
	s_waitcnt vmcnt(0)
.LBB0_493:
	v_mul_f32_e32 v101, 0x3e16c740, v100
	v_lshlrev_b64 v[102:103], 11, v[98:99]
	v_cndmask_b32_e64 v124, v100, v101, s[52:53]
	v_lshlrev_b64 v[100:101], 10, v[98:99]
	v_lshl_add_u64 v[118:119], s[88:89], 0, v[102:103]
	v_lshlrev_b64 v[104:105], 12, v[98:99]
	v_lshl_add_u64 v[116:117], s[34:35], 0, v[102:103]
	v_lshlrev_b64 v[102:103], 13, v[98:99]
	v_lshl_add_u64 v[152:153], v[148:149], 0, v[104:105]
	v_lshl_add_u64 v[108:109], s[2:3], 0, v[100:101]
	v_lshl_add_u64 v[154:155], s[28:29], 0, v[102:103]
	v_pk_mul_f32 v[120:121], v[96:97], v[124:125] op_sel_hi:[1,0]
	v_pk_mul_f32 v[158:159], v[94:95], v[124:125] op_sel_hi:[1,0]
	v_pk_mul_f32 v[160:161], v[92:93], v[124:125] op_sel_hi:[1,0]
	v_pk_mul_f32 v[162:163], v[90:91], v[124:125] op_sel_hi:[1,0]
	s_cmp_lt_i32 s62, 4
	s_mov_b64 s[50:51], -1
	s_cbranch_scc1 .LBB0_512
	s_cmp_lt_i32 s62, 6
	s_cbranch_scc1 .LBB0_503
	s_cmp_gt_i32 s62, 6
	s_cbranch_scc0 .LBB0_497
	v_max_f32_e32 v91, v162, v162
	v_max_f32_e32 v95, v160, v160
	v_max_f32_e32 v90, v158, v158
	v_max_f32_e32 v92, 0, v91
	v_max_f32_e32 v91, v159, v159
	v_max_f32_e32 v93, v163, v163
	v_max_f32_e32 v94, v120, v120
	v_max_f32_e32 v96, 0, v95
	v_max_f32_e32 v95, v121, v121
	v_max_f32_e32 v97, v161, v161
	v_max_f32_e32 v90, 0, v90
	v_max_f32_e32 v91, 0, v91
	v_max_f32_e32 v93, 0, v93
	v_max_f32_e32 v94, 0, v94
	v_max_f32_e32 v95, 0, v95
	v_max_f32_e32 v97, 0, v97
	v_pk_mul_f32 v[90:91], v[90:91], v[90:91]
	v_pk_mul_f32 v[92:93], v[92:93], v[92:93]
	v_pk_mul_f32 v[94:95], v[94:95], v[94:95]
	v_pk_mul_f32 v[96:97], v[96:97], v[96:97]
	v_ashrrev_i32_e32 v147, 31, v146
	v_lshl_add_u64 v[102:103], v[146:147], 1, v[154:155]
	v_cvt_pk_bf16_f32 v90, v90, v91
	v_cvt_pk_bf16_f32 v91, v94, v95
	v_cvt_pk_bf16_f32 v92, v92, v93
	v_cvt_pk_bf16_f32 v93, v96, v97
	global_store_dwordx4 v[102:103], v[90:93], off
	s_mov_b64 s[50:51], 0

.LBB0_555:
	s_waitcnt lgkmcnt(0)
	v_mov_b32_e32 v98, v216
	v_mov_b32_e32 v99, v217
	v_ffbh_u32_e32 v100, v99
	v_min_u32_e32 v100, 32, v100
	v_lshlrev_b64 v[98:99], v100, v[98:99]
	v_min_u32_e32 v98, 1, v98
	v_or_b32_e32 v98, v99, v98
	v_cvt_f32_u32_e32 v98, v98
	v_sub_u32_e32 v99, 32, v100
	v_ldexp_f32 v98, v98, v99
	v_fmaak_f32 v98, v192, v98, 0x358637bd
	v_rsq_f32_e32 v100, v98
	v_add_u32_e32 v98, 32, v144
	v_ashrrev_i32_e32 v99, 31, v98
	s_cbranch_execz .LBB0_492
	s_branch .LBB0_493

.LBB0_622:
	v_lshl_add_u64 v[84:85], v[82:83], 2, s[66:67]
	global_load_dword v84, v[84:85], off
	s_waitcnt vmcnt(0)
.LBB0_623:
	v_mul_f32_e32 v85, 0x3e16c740, v84
	v_lshlrev_b64 v[86:87], 11, v[82:83]
	v_cndmask_b32_e64 v104, v84, v85, s[52:53]
	v_lshlrev_b64 v[84:85], 10, v[82:83]
	v_lshl_add_u64 v[100:101], s[88:89], 0, v[86:87]
	v_lshlrev_b64 v[88:89], 12, v[82:83]
	v_lshl_add_u64 v[98:99], s[34:35], 0, v[86:87]
	v_lshlrev_b64 v[86:87], 13, v[82:83]
	v_lshl_add_u64 v[108:109], v[148:149], 0, v[88:89]
	v_lshl_add_u64 v[92:93], s[2:3], 0, v[84:85]
	v_lshl_add_u64 v[110:111], s[28:29], 0, v[86:87]
	v_pk_mul_f32 v[102:103], v[80:81], v[104:105] op_sel_hi:[1,0]
	v_pk_mul_f32 v[116:117], v[78:79], v[104:105] op_sel_hi:[1,0]
	v_pk_mul_f32 v[118:119], v[76:77], v[104:105] op_sel_hi:[1,0]
	v_pk_mul_f32 v[120:121], v[74:75], v[104:105] op_sel_hi:[1,0]
	s_cmp_lt_i32 s62, 4
	s_mov_b64 s[50:51], -1
	s_cbranch_scc1 .LBB0_642
	s_cmp_lt_i32 s62, 6
	s_cbranch_scc1 .LBB0_633
	s_cmp_gt_i32 s62, 6
	s_cbranch_scc0 .LBB0_627
	v_max_f32_e32 v75, v120, v120
	v_max_f32_e32 v79, v118, v118
	v_max_f32_e32 v74, v116, v116
	v_max_f32_e32 v76, 0, v75
	v_max_f32_e32 v75, v117, v117
	v_max_f32_e32 v77, v121, v121
	v_max_f32_e32 v78, v102, v102
	v_max_f32_e32 v80, 0, v79
	v_max_f32_e32 v79, v103, v103
	v_max_f32_e32 v81, v119, v119
	v_max_f32_e32 v74, 0, v74
	v_max_f32_e32 v75, 0, v75
	v_max_f32_e32 v77, 0, v77
	v_max_f32_e32 v78, 0, v78
	v_max_f32_e32 v79, 0, v79
	v_max_f32_e32 v81, 0, v81
	v_pk_mul_f32 v[74:75], v[74:75], v[74:75]
	v_pk_mul_f32 v[76:77], v[76:77], v[76:77]
	v_pk_mul_f32 v[78:79], v[78:79], v[78:79]
	v_pk_mul_f32 v[80:81], v[80:81], v[80:81]
	v_ashrrev_i32_e32 v147, 31, v146
	v_lshl_add_u64 v[86:87], v[146:147], 1, v[110:111]
	v_cvt_pk_bf16_f32 v74, v74, v75
	v_cvt_pk_bf16_f32 v75, v78, v79
	v_cvt_pk_bf16_f32 v76, v76, v77
	v_cvt_pk_bf16_f32 v77, v80, v81
	global_store_dwordx4 v[86:87], v[74:77], off
	s_mov_b64 s[50:51], 0

.LBB0_685:
	s_waitcnt lgkmcnt(0)
	v_mov_b32_e32 v82, v218
	v_mov_b32_e32 v83, v219
	v_ffbh_u32_e32 v84, v83
	v_min_u32_e32 v84, 32, v84
	v_lshlrev_b64 v[82:83], v84, v[82:83]
	v_min_u32_e32 v82, 1, v82
	v_or_b32_e32 v82, v83, v82
	v_cvt_f32_u32_e32 v82, v82
	v_sub_u32_e32 v83, 32, v84
	v_ldexp_f32 v82, v82, v83
	v_fmaak_f32 v82, v192, v82, 0x358637bd
	v_rsq_f32_e32 v84, v82
	v_add_u32_e32 v82, 48, v144
	v_ashrrev_i32_e32 v83, 31, v82
	s_cbranch_execz .LBB0_622
	s_branch .LBB0_623

.LBB0_752:
	v_lshl_add_u64 v[68:69], v[66:67], 2, s[66:67]
	global_load_dword v68, v[68:69], off
	s_waitcnt vmcnt(0)
.LBB0_753:
	v_mul_f32_e32 v69, 0x3e16c740, v68
	v_lshlrev_b64 v[70:71], 11, v[66:67]
	v_cndmask_b32_e64 v88, v68, v69, s[52:53]
	v_lshlrev_b64 v[68:69], 10, v[66:67]
	v_lshl_add_u64 v[84:85], s[88:89], 0, v[70:71]
	v_lshlrev_b64 v[72:73], 12, v[66:67]
	v_lshl_add_u64 v[82:83], s[34:35], 0, v[70:71]
	v_lshlrev_b64 v[70:71], 13, v[66:67]
	v_lshl_add_u64 v[92:93], v[148:149], 0, v[72:73]
	v_lshl_add_u64 v[76:77], s[2:3], 0, v[68:69]
	v_lshl_add_u64 v[94:95], s[28:29], 0, v[70:71]
	v_pk_mul_f32 v[86:87], v[64:65], v[88:89] op_sel_hi:[1,0]
	v_pk_mul_f32 v[98:99], v[62:63], v[88:89] op_sel_hi:[1,0]
	v_pk_mul_f32 v[100:101], v[60:61], v[88:89] op_sel_hi:[1,0]
	v_pk_mul_f32 v[102:103], v[58:59], v[88:89] op_sel_hi:[1,0]
	s_cmp_lt_i32 s62, 4
	s_mov_b64 s[50:51], -1
	s_cbranch_scc1 .LBB0_772
	s_cmp_lt_i32 s62, 6
	s_cbranch_scc1 .LBB0_763
	s_cmp_gt_i32 s62, 6
	s_cbranch_scc0 .LBB0_757
	v_max_f32_e32 v59, v102, v102
	v_max_f32_e32 v63, v100, v100
	v_max_f32_e32 v58, v98, v98
	v_max_f32_e32 v60, 0, v59
	v_max_f32_e32 v59, v99, v99
	v_max_f32_e32 v61, v103, v103
	v_max_f32_e32 v62, v86, v86
	v_max_f32_e32 v64, 0, v63
	v_max_f32_e32 v63, v87, v87
	v_max_f32_e32 v65, v101, v101
	v_max_f32_e32 v58, 0, v58
	v_max_f32_e32 v59, 0, v59
	v_max_f32_e32 v61, 0, v61
	v_max_f32_e32 v62, 0, v62
	v_max_f32_e32 v63, 0, v63
	v_max_f32_e32 v65, 0, v65
	v_pk_mul_f32 v[58:59], v[58:59], v[58:59]
	v_pk_mul_f32 v[60:61], v[60:61], v[60:61]
	v_pk_mul_f32 v[62:63], v[62:63], v[62:63]
	v_pk_mul_f32 v[64:65], v[64:65], v[64:65]
	v_ashrrev_i32_e32 v147, 31, v146
	v_lshl_add_u64 v[70:71], v[146:147], 1, v[94:95]
	v_cvt_pk_bf16_f32 v58, v58, v59
	v_cvt_pk_bf16_f32 v59, v62, v63
	v_cvt_pk_bf16_f32 v60, v60, v61
	v_cvt_pk_bf16_f32 v61, v64, v65
	global_store_dwordx4 v[70:71], v[58:61], off
	s_mov_b64 s[50:51], 0

.LBB0_815:
	s_waitcnt lgkmcnt(0)
	v_mov_b32_e32 v66, v220
	v_mov_b32_e32 v67, v221
	v_ffbh_u32_e32 v68, v67
	v_min_u32_e32 v68, 32, v68
	v_lshlrev_b64 v[66:67], v68, v[66:67]
	v_min_u32_e32 v66, 1, v66
	v_or_b32_e32 v66, v67, v66
	v_cvt_f32_u32_e32 v66, v66
	v_sub_u32_e32 v67, 32, v68
	v_ldexp_f32 v66, v66, v67
	v_fmaak_f32 v66, v192, v66, 0x358637bd
	v_rsq_f32_e32 v68, v66
	v_add_u32_e32 v66, 0x80, v144
	v_ashrrev_i32_e32 v67, 31, v66
	s_cbranch_execz .LBB0_752
	s_branch .LBB0_753

.LBB0_882:
	v_lshl_add_u64 v[52:53], v[50:51], 2, s[66:67]
	global_load_dword v52, v[52:53], off
	s_waitcnt vmcnt(0)
.LBB0_883:
	v_mul_f32_e32 v53, 0x3e16c740, v52
	v_lshlrev_b64 v[54:55], 11, v[50:51]
	v_cndmask_b32_e64 v72, v52, v53, s[52:53]
	v_lshlrev_b64 v[52:53], 10, v[50:51]
	v_lshl_add_u64 v[68:69], s[88:89], 0, v[54:55]
	v_lshlrev_b64 v[56:57], 12, v[50:51]
	v_lshl_add_u64 v[66:67], s[34:35], 0, v[54:55]
	v_lshlrev_b64 v[54:55], 13, v[50:51]
	v_lshl_add_u64 v[76:77], v[148:149], 0, v[56:57]
	v_lshl_add_u64 v[60:61], s[2:3], 0, v[52:53]
	v_lshl_add_u64 v[78:79], s[28:29], 0, v[54:55]
	v_pk_mul_f32 v[70:71], v[48:49], v[72:73] op_sel_hi:[1,0]
	v_pk_mul_f32 v[82:83], v[46:47], v[72:73] op_sel_hi:[1,0]
	v_pk_mul_f32 v[84:85], v[44:45], v[72:73] op_sel_hi:[1,0]
	v_pk_mul_f32 v[86:87], v[42:43], v[72:73] op_sel_hi:[1,0]
	s_cmp_lt_i32 s62, 4
	s_mov_b64 s[50:51], -1
	s_cbranch_scc1 .LBB0_902
	s_cmp_lt_i32 s62, 6
	s_cbranch_scc1 .LBB0_893
	s_cmp_gt_i32 s62, 6
	s_cbranch_scc0 .LBB0_887
	v_max_f32_e32 v43, v86, v86
	v_max_f32_e32 v47, v84, v84
	v_max_f32_e32 v42, v82, v82
	v_max_f32_e32 v44, 0, v43
	v_max_f32_e32 v43, v83, v83
	v_max_f32_e32 v45, v87, v87
	v_max_f32_e32 v46, v70, v70
	v_max_f32_e32 v48, 0, v47
	v_max_f32_e32 v47, v71, v71
	v_max_f32_e32 v49, v85, v85
	v_max_f32_e32 v42, 0, v42
	v_max_f32_e32 v43, 0, v43
	v_max_f32_e32 v45, 0, v45
	v_max_f32_e32 v46, 0, v46
	v_max_f32_e32 v47, 0, v47
	v_max_f32_e32 v49, 0, v49
	v_pk_mul_f32 v[42:43], v[42:43], v[42:43]
	v_pk_mul_f32 v[44:45], v[44:45], v[44:45]
	v_pk_mul_f32 v[46:47], v[46:47], v[46:47]
	v_pk_mul_f32 v[48:49], v[48:49], v[48:49]
	v_ashrrev_i32_e32 v147, 31, v146
	v_lshl_add_u64 v[54:55], v[146:147], 1, v[78:79]
	v_cvt_pk_bf16_f32 v42, v42, v43
	v_cvt_pk_bf16_f32 v43, v46, v47
	v_cvt_pk_bf16_f32 v44, v44, v45
	v_cvt_pk_bf16_f32 v45, v48, v49
	global_store_dwordx4 v[54:55], v[42:45], off
	s_mov_b64 s[50:51], 0

.LBB0_945:
	s_waitcnt lgkmcnt(0)
	v_mov_b32_e32 v50, v222
	v_mov_b32_e32 v51, v223
	v_ffbh_u32_e32 v52, v51
	v_min_u32_e32 v52, 32, v52
	v_lshlrev_b64 v[50:51], v52, v[50:51]
	v_min_u32_e32 v50, 1, v50
	v_or_b32_e32 v50, v51, v50
	v_cvt_f32_u32_e32 v50, v50
	v_sub_u32_e32 v51, 32, v52
	v_ldexp_f32 v50, v50, v51
	v_fmaak_f32 v50, v192, v50, 0x358637bd
	v_rsq_f32_e32 v52, v50
	v_add_u32_e32 v50, 0x90, v144
	v_ashrrev_i32_e32 v51, 31, v50
	s_cbranch_execz .LBB0_882
	s_branch .LBB0_883

.LBB0_1012:
	v_lshl_add_u64 v[36:37], v[34:35], 2, s[66:67]
	global_load_dword v36, v[36:37], off
	s_waitcnt vmcnt(0)
.LBB0_1013:
	v_mul_f32_e32 v37, 0x3e16c740, v36
	v_lshlrev_b64 v[38:39], 11, v[34:35]
	v_cndmask_b32_e64 v56, v36, v37, s[52:53]
	v_lshlrev_b64 v[36:37], 10, v[34:35]
	v_lshl_add_u64 v[52:53], s[88:89], 0, v[38:39]
	v_lshlrev_b64 v[40:41], 12, v[34:35]
	v_lshl_add_u64 v[50:51], s[34:35], 0, v[38:39]
	v_lshlrev_b64 v[38:39], 13, v[34:35]
	v_lshl_add_u64 v[60:61], v[148:149], 0, v[40:41]
	v_lshl_add_u64 v[44:45], s[2:3], 0, v[36:37]
	v_lshl_add_u64 v[62:63], s[28:29], 0, v[38:39]
	v_pk_mul_f32 v[54:55], v[32:33], v[56:57] op_sel_hi:[1,0]
	v_pk_mul_f32 v[66:67], v[30:31], v[56:57] op_sel_hi:[1,0]
	v_pk_mul_f32 v[68:69], v[28:29], v[56:57] op_sel_hi:[1,0]
	v_pk_mul_f32 v[70:71], v[26:27], v[56:57] op_sel_hi:[1,0]
	s_cmp_lt_i32 s62, 4
	s_mov_b64 s[50:51], -1
	s_cbranch_scc1 .LBB0_1032
	s_cmp_lt_i32 s62, 6
	s_cbranch_scc1 .LBB0_1023
	s_cmp_gt_i32 s62, 6
	s_cbranch_scc0 .LBB0_1017
	v_max_f32_e32 v27, v70, v70
	v_max_f32_e32 v31, v68, v68
	v_max_f32_e32 v26, v66, v66
	v_max_f32_e32 v28, 0, v27
	v_max_f32_e32 v27, v67, v67
	v_max_f32_e32 v29, v71, v71
	v_max_f32_e32 v30, v54, v54
	v_max_f32_e32 v32, 0, v31
	v_max_f32_e32 v31, v55, v55
	v_max_f32_e32 v33, v69, v69
	v_max_f32_e32 v26, 0, v26
	v_max_f32_e32 v27, 0, v27
	v_max_f32_e32 v29, 0, v29
	v_max_f32_e32 v30, 0, v30
	v_max_f32_e32 v31, 0, v31
	v_max_f32_e32 v33, 0, v33
	v_pk_mul_f32 v[26:27], v[26:27], v[26:27]
	v_pk_mul_f32 v[28:29], v[28:29], v[28:29]
	v_pk_mul_f32 v[30:31], v[30:31], v[30:31]
	v_pk_mul_f32 v[32:33], v[32:33], v[32:33]
	v_ashrrev_i32_e32 v147, 31, v146
	v_lshl_add_u64 v[38:39], v[146:147], 1, v[62:63]
	v_cvt_pk_bf16_f32 v26, v26, v27
	v_cvt_pk_bf16_f32 v27, v30, v31
	v_cvt_pk_bf16_f32 v28, v28, v29
	v_cvt_pk_bf16_f32 v29, v32, v33
	global_store_dwordx4 v[38:39], v[26:29], off
	s_mov_b64 s[50:51], 0

.LBB0_1075:
	s_waitcnt lgkmcnt(0)
	v_mov_b32_e32 v34, v224
	v_mov_b32_e32 v35, v225
	v_ffbh_u32_e32 v36, v35
	v_min_u32_e32 v36, 32, v36
	v_lshlrev_b64 v[34:35], v36, v[34:35]
	v_min_u32_e32 v34, 1, v34
	v_or_b32_e32 v34, v35, v34
	v_cvt_f32_u32_e32 v34, v34
	v_sub_u32_e32 v35, 32, v36
	v_ldexp_f32 v34, v34, v35
	v_fmaak_f32 v34, v192, v34, 0x358637bd
	v_rsq_f32_e32 v36, v34
	v_add_u32_e32 v34, 0xa0, v144
	v_ashrrev_i32_e32 v35, 31, v34
	s_cbranch_execz .LBB0_1012
	s_branch .LBB0_1013

.LBB0_1142:
	v_lshl_add_u64 v[20:21], v[18:19], 2, s[66:67]
	global_load_dword v20, v[20:21], off
	s_waitcnt vmcnt(0)
.LBB0_1143:
	v_mul_f32_e32 v21, 0x3e16c740, v20
	v_lshlrev_b64 v[22:23], 11, v[18:19]
	v_cndmask_b32_e64 v40, v20, v21, s[52:53]
	v_lshlrev_b64 v[20:21], 10, v[18:19]
	v_lshl_add_u64 v[36:37], s[88:89], 0, v[22:23]
	v_lshlrev_b64 v[24:25], 12, v[18:19]
	v_lshl_add_u64 v[34:35], s[34:35], 0, v[22:23]
	v_lshlrev_b64 v[22:23], 13, v[18:19]
	v_lshl_add_u64 v[44:45], v[148:149], 0, v[24:25]
	v_lshl_add_u64 v[28:29], s[2:3], 0, v[20:21]
	v_lshl_add_u64 v[46:47], s[28:29], 0, v[22:23]
	v_pk_mul_f32 v[38:39], v[16:17], v[40:41] op_sel_hi:[1,0]
	v_pk_mul_f32 v[50:51], v[14:15], v[40:41] op_sel_hi:[1,0]
	v_pk_mul_f32 v[52:53], v[12:13], v[40:41] op_sel_hi:[1,0]
	v_pk_mul_f32 v[54:55], v[10:11], v[40:41] op_sel_hi:[1,0]
	s_cmp_lt_i32 s62, 4
	s_mov_b64 s[28:29], -1
	s_cbranch_scc1 .LBB0_1162
	s_cmp_lt_i32 s62, 6
	s_cbranch_scc1 .LBB0_1153
	s_cmp_gt_i32 s62, 6
	s_cbranch_scc0 .LBB0_1147
	v_max_f32_e32 v11, v54, v54
	v_max_f32_e32 v15, v52, v52
	v_max_f32_e32 v10, v50, v50
	v_max_f32_e32 v12, 0, v11
	v_max_f32_e32 v11, v51, v51
	v_max_f32_e32 v13, v55, v55
	v_max_f32_e32 v14, v38, v38
	v_max_f32_e32 v16, 0, v15
	v_max_f32_e32 v15, v39, v39
	v_max_f32_e32 v17, v53, v53
	v_max_f32_e32 v10, 0, v10
	v_max_f32_e32 v11, 0, v11
	v_max_f32_e32 v13, 0, v13
	v_max_f32_e32 v14, 0, v14
	v_max_f32_e32 v15, 0, v15
	v_max_f32_e32 v17, 0, v17
	v_pk_mul_f32 v[10:11], v[10:11], v[10:11]
	v_pk_mul_f32 v[12:13], v[12:13], v[12:13]
	v_pk_mul_f32 v[14:15], v[14:15], v[14:15]
	v_pk_mul_f32 v[16:17], v[16:17], v[16:17]
	v_ashrrev_i32_e32 v147, 31, v146
	v_lshl_add_u64 v[22:23], v[146:147], 1, v[46:47]
	v_cvt_pk_bf16_f32 v10, v10, v11
	v_cvt_pk_bf16_f32 v11, v14, v15
	v_cvt_pk_bf16_f32 v12, v12, v13
	v_cvt_pk_bf16_f32 v13, v16, v17
	global_store_dwordx4 v[22:23], v[10:13], off
	s_mov_b64 s[28:29], 0

.LBB0_1206:
	s_waitcnt lgkmcnt(0)
	v_mov_b32_e32 v18, v226
	v_mov_b32_e32 v19, v227
	v_ffbh_u32_e32 v20, v19
	v_min_u32_e32 v20, 32, v20
	v_lshlrev_b64 v[18:19], v20, v[18:19]
	v_min_u32_e32 v18, 1, v18
	v_or_b32_e32 v18, v19, v18
	v_cvt_f32_u32_e32 v18, v18
	v_sub_u32_e32 v19, 32, v20
	v_ldexp_f32 v18, v18, v19
	v_fmaak_f32 v18, v192, v18, 0x358637bd
	v_rsq_f32_e32 v20, v18
	v_add_u32_e32 v18, 0xb0, v144
	v_ashrrev_i32_e32 v19, 31, v18
	s_cbranch_execz .LBB0_1142
	s_branch .LBB0_1143

.Lmf_pre:
	v_max3_f32 v1, v66, v67, v68
	v_max3_f32 v170, v69, v70, v71
	v_max3_f32 v1, v1, v72, v73
	v_max3_f32 v170, v170, v74, v75
	v_max3_f32 v1, v1, v76, v77
	v_max3_f32 v170, v170, v78, v79
	v_max3_f32 v1, v1, v80, v81
	v_max3_f32 v170, v170, v82, v83
	v_max3_f32 v1, v1, v84, v85
	v_max3_f32 v170, v170, v86, v87
	v_max3_f32 v1, v1, v88, v89
	v_max3_f32 v170, v170, v90, v91
	v_max3_f32 v1, v1, v92, v93
	v_max3_f32 v170, v170, v94, v95
	v_max3_f32 v1, v1, v96, v97
	v_max_f32_e32 v1, v1, v170
	v_mov_b32_e32 v170, v1
	v_mov_b32_e32 v239, 0xc000
	v_cndmask_b32_e64 v238, v239, 0, s[40:41]
	v_permlane32_swap_b32_e32 v1, v170
	v_add_u32_e32 v238, v229, v238
	v_max_f32_e32 v1, v1, v170
	v_mov_b32_e32 v202, v1
	v_sub_f32_e32 v66, v66, v1
	v_sub_f32_e32 v67, v67, v1
	v_sub_f32_e32 v68, v68, v1
	v_sub_f32_e32 v69, v69, v1
	v_sub_f32_e32 v70, v70, v1
	v_sub_f32_e32 v71, v71, v1
	v_sub_f32_e32 v72, v72, v1
	v_sub_f32_e32 v73, v73, v1
	v_sub_f32_e32 v74, v74, v1
	v_sub_f32_e32 v75, v75, v1
	v_sub_f32_e32 v76, v76, v1
	v_sub_f32_e32 v77, v77, v1
	v_sub_f32_e32 v78, v78, v1
	v_sub_f32_e32 v79, v79, v1
	v_sub_f32_e32 v80, v80, v1
	v_sub_f32_e32 v81, v81, v1
	v_sub_f32_e32 v82, v82, v1
	v_sub_f32_e32 v83, v83, v1
	v_sub_f32_e32 v84, v84, v1
	v_sub_f32_e32 v85, v85, v1
	v_sub_f32_e32 v86, v86, v1
	v_sub_f32_e32 v87, v87, v1
	v_sub_f32_e32 v88, v88, v1
	v_sub_f32_e32 v89, v89, v1
	v_sub_f32_e32 v90, v90, v1
	v_sub_f32_e32 v91, v91, v1
	v_sub_f32_e32 v92, v92, v1
	v_sub_f32_e32 v93, v93, v1
	v_sub_f32_e32 v94, v94, v1
	v_sub_f32_e32 v95, v95, v1
	v_sub_f32_e32 v96, v96, v1
	v_sub_f32_e32 v97, v97, v1
	v_sub_f32_e32 v146, 0, v1
	v_sub_f32_e32 v147, 0, v1
	v_sub_f32_e32 v148, 0, v1
	v_sub_f32_e32 v149, 0, v1
	v_sub_f32_e32 v150, 0, v1
	v_sub_f32_e32 v151, 0, v1
	v_sub_f32_e32 v152, 0, v1
	v_sub_f32_e32 v153, 0, v1
	v_sub_f32_e32 v154, 0, v1
	v_sub_f32_e32 v155, 0, v1
	v_sub_f32_e32 v156, 0, v1
	v_sub_f32_e32 v157, 0, v1
	v_sub_f32_e32 v158, 0, v1
	v_sub_f32_e32 v159, 0, v1
	v_sub_f32_e32 v160, 0, v1
	v_sub_f32_e32 v161, 0, v1
.Lmf_loop:
	ds_read_b128 v[162:165], v216 offset:13312
	ds_read_b128 v[166:169], v216 offset:19968
	ds_read_b128 v[172:175], v216 offset:13344
	ds_read_b128 v[176:179], v216 offset:20000
	v_add_u32_e32 v196, s19, v226
	v_subrev_u32_e32 v196, 64, v196
	v_mad_i64_i32 v[230:231], s[14:15], v196, s90, v[204:205]
	global_load_dwordx4 v[130:133], v[230:231], off
	s_cmp_lg_u64 s[40:41], 0
	s_cbranch_scc0 .Lmf_nok1_0
	v_add_u32_e32 v196, s19, v227
	v_subrev_u32_e32 v196, 64, v196
	v_mad_i64_i32 v[230:231], s[14:15], v196, s90, v[206:207]
.Lmf_nok1_0:
	global_load_dwordx4 v[134:137], v[230:231], off
	s_add_i32 s84, s19, 0xffffff80
	v_lshl_add_u64 v[230:231], s[84:85], 1, v[200:201]
	global_load_dwordx4 v[142:145], v[230:231], off
	v_exp_f32_e32 v66, v66
	v_exp_f32_e32 v67, v67
	v_exp_f32_e32 v68, v68
	v_exp_f32_e32 v69, v69
	s_waitcnt lgkmcnt(3)
	v_mfma_f32_32x32x16_bf16 v[34:49], v[162:165], v[98:101], v[146:161]
	ds_read_b128 v[180:183], v216 offset:13376
	v_add_f32_e32 v171, v66, v171
	v_exp_f32_e32 v70, v70
	v_exp_f32_e32 v71, v71
	s_waitcnt lgkmcnt(3)
	v_mfma_f32_32x32x16_bf16 v[50:65], v[166:169], v[98:101], v[146:161]
	ds_read_b128 v[184:187], v216 offset:20032
	v_add_f32_e32 v171, v68, v171
	v_exp_f32_e32 v72, v72
	v_add_f32_e32 v197, v67, v69
	v_exp_f32_e32 v73, v73
	s_waitcnt lgkmcnt(3)
	v_mfma_f32_32x32x16_bf16 v[34:49], v[172:175], v[102:105], v[34:49]
	ds_read_b128 v[188:191], v216 offset:13408
	v_add_f32_e32 v171, v70, v171
	v_add_f32_e32 v197, v71, v197
	v_cvt_pk_bf16_f32 v66, v66, v67
	v_add_f32_e32 v171, v72, v171
	v_cvt_pk_bf16_f32 v67, v68, v69
	v_add_f32_e32 v197, v73, v197
	v_cvt_pk_bf16_f32 v68, v70, v71
	s_waitcnt lgkmcnt(3)
	v_mfma_f32_32x32x16_bf16 v[50:65], v[176:179], v[102:105], v[50:65]
	ds_read_b128 v[192:195], v216 offset:20064
	v_cvt_pk_bf16_f32 v69, v72, v73
	v_exp_f32_e32 v74, v74
	v_exp_f32_e32 v75, v75
	v_exp_f32_e32 v76, v76
	s_waitcnt lgkmcnt(3)
	v_mfma_f32_32x32x16_bf16 v[34:49], v[180:183], v[106:109], v[34:49]
	ds_read_b128 v[162:165], v216 offset:13440
	v_exp_f32_e32 v77, v77
	v_add_f32_e32 v171, v74, v171
	v_exp_f32_e32 v78, v78
	s_waitcnt lgkmcnt(3)
	v_mfma_f32_32x32x16_bf16 v[50:65], v[184:187], v[106:109], v[50:65]
	ds_read_b128 v[166:169], v216 offset:20096
	v_add_f32_e32 v197, v75, v197
	v_exp_f32_e32 v79, v79
	v_add_f32_e32 v171, v76, v171
	v_exp_f32_e32 v80, v80
	s_waitcnt lgkmcnt(3)
	v_mfma_f32_32x32x16_bf16 v[34:49], v[188:191], v[110:113], v[34:49]
	ds_read_b128 v[172:175], v216 offset:13472
	v_add_f32_e32 v197, v77, v197
	v_exp_f32_e32 v81, v81
	v_add_f32_e32 v171, v78, v171
	v_add_f32_e32 v197, v79, v197
	v_cvt_pk_bf16_f32 v74, v74, v75
	v_add_f32_e32 v171, v80, v171
	s_waitcnt lgkmcnt(3)
	v_mfma_f32_32x32x16_bf16 v[50:65], v[192:195], v[110:113], v[50:65]
	ds_read_b128 v[176:179], v216 offset:20128
	v_cvt_pk_bf16_f32 v75, v76, v77
	v_add_f32_e32 v197, v81, v197
	v_cvt_pk_bf16_f32 v76, v78, v79
	v_cvt_pk_bf16_f32 v77, v80, v81
	v_exp_f32_e32 v82, v82
	s_waitcnt lgkmcnt(3)
	v_mfma_f32_32x32x16_bf16 v[34:49], v[162:165], v[114:117], v[34:49]
	ds_read_b128 v[180:183], v217 offset:26624
	v_exp_f32_e32 v83, v83
	v_exp_f32_e32 v84, v84
	v_exp_f32_e32 v85, v85
	s_waitcnt lgkmcnt(3)
	v_mfma_f32_32x32x16_bf16 v[50:65], v[166:169], v[114:117], v[50:65]
	ds_read_b128 v[184:187], v217 offset:31232
	v_add_f32_e32 v171, v82, v171
	v_exp_f32_e32 v86, v86
	v_add_f32_e32 v197, v83, v197
	v_exp_f32_e32 v87, v87
	s_waitcnt lgkmcnt(3)
	v_mfma_f32_32x32x16_bf16 v[34:49], v[172:175], v[118:121], v[34:49]
	ds_read_b128 v[188:191], v217 offset:26656
	v_add_f32_e32 v171, v84, v171
	v_exp_f32_e32 v88, v88
	v_add_f32_e32 v197, v85, v197
	v_exp_f32_e32 v89, v89
	v_add_f32_e32 v171, v86, v171
	s_waitcnt lgkmcnt(3)
	v_mfma_f32_32x32x16_bf16 v[50:65], v[176:179], v[118:121], v[50:65]
	ds_read_b128 v[192:195], v217 offset:31264
	v_add_f32_e32 v197, v87, v197
	v_cvt_pk_bf16_f32 v82, v82, v83
	v_add_f32_e32 v171, v88, v171
	v_cvt_pk_bf16_f32 v83, v84, v85
	v_add_f32_e32 v197, v89, v197
	v_cvt_pk_bf16_f32 v84, v86, v87
	s_waitcnt lgkmcnt(3)
	v_mfma_f32_32x32x16_bf16 v[18:33], v[180:183], v[66:69], v[18:33]
	ds_read_b128 v[162:165], v217 offset:26688
	v_cvt_pk_bf16_f32 v85, v88, v89
	v_exp_f32_e32 v90, v90
	v_exp_f32_e32 v91, v91
	v_exp_f32_e32 v92, v92
	s_waitcnt lgkmcnt(3)
	v_mfma_f32_32x32x16_bf16 v[2:17], v[184:187], v[66:69], v[2:17]
	ds_read_b128 v[166:169], v217 offset:31296
	v_exp_f32_e32 v93, v93
	v_add_f32_e32 v171, v90, v171
	v_exp_f32_e32 v94, v94
	s_waitcnt lgkmcnt(3)
	v_mfma_f32_32x32x16_bf16 v[18:33], v[188:191], v[74:77], v[18:33]
	ds_read_b128 v[172:175], v217 offset:26720
	v_add_f32_e32 v197, v91, v197
	v_exp_f32_e32 v95, v95
	v_add_f32_e32 v171, v92, v171
	v_exp_f32_e32 v96, v96
	v_add_f32_e32 v197, v93, v197
	s_waitcnt lgkmcnt(3)
	v_mfma_f32_32x32x16_bf16 v[2:17], v[192:195], v[74:77], v[2:17]
	ds_read_b128 v[176:179], v217 offset:31328
	s_waitcnt vmcnt(3)
	v_add_u32_e32 v196, 0x8800, v215
	ds_write_b128 v228, v[122:125]
	ds_write_b128 v238, v[126:129]
	ds_write2_b64 v196, v[138:139], v[140:141] offset0:128 offset1:130
	v_exp_f32_e32 v97, v97
	v_add_f32_e32 v171, v94, v171
	v_add_f32_e32 v197, v95, v197
	v_cvt_pk_bf16_f32 v90, v90, v91
	v_add_f32_e32 v171, v96, v171
	s_waitcnt lgkmcnt(6)
	v_mfma_f32_32x32x16_bf16 v[18:33], v[162:165], v[82:85], v[18:33]
	v_cvt_pk_bf16_f32 v91, v92, v93
	v_add_f32_e32 v197, v97, v197
	v_cvt_pk_bf16_f32 v92, v94, v95
	v_cvt_pk_bf16_f32 v93, v96, v97
	v_max3_f32 v1, v34, v35, v36
	v_max3_f32 v170, v37, v38, v39
	s_waitcnt lgkmcnt(5)
	v_mfma_f32_32x32x16_bf16 v[2:17], v[166:169], v[82:85], v[2:17]
	v_max3_f32 v1, v1, v40, v41
	v_max3_f32 v170, v170, v42, v43
	v_max3_f32 v1, v1, v44, v45
	v_max3_f32 v170, v170, v46, v47
	v_max3_f32 v1, v1, v48, v49
	v_max3_f32 v170, v170, v50, v51
	s_waitcnt lgkmcnt(4)
	v_mfma_f32_32x32x16_bf16 v[18:33], v[172:175], v[90:93], v[18:33]
	v_max3_f32 v1, v1, v52, v53
	v_max3_f32 v170, v170, v54, v55
	v_max3_f32 v1, v1, v56, v57
	v_max3_f32 v170, v170, v58, v59
	v_max3_f32 v1, v1, v60, v61
	v_max3_f32 v170, v170, v62, v63
	v_max3_f32 v1, v1, v64, v65
	s_waitcnt lgkmcnt(3)
	v_mfma_f32_32x32x16_bf16 v[2:17], v[176:179], v[90:93], v[2:17]
	v_max_f32_e32 v1, v1, v170
	v_mov_b32_e32 v170, v1
	v_add_f32_e32 v171, v197, v171
	s_nop 0
	v_permlane32_swap_b32_e32 v1, v170
	v_max_f32_e32 v1, v1, v170
	v_cmp_lt_f32_e32 vcc, s93, v1
	s_cbranch_vccnz .Lmf_slow_0
.Lmf_join_0:
	s_waitcnt lgkmcnt(0)
	s_barrier
	ds_read_b128 v[162:165], v216 offset:0
	ds_read_b128 v[166:169], v216 offset:6656
	ds_read_b128 v[172:175], v216 offset:32
	ds_read_b128 v[176:179], v216 offset:6688
	v_add_u32_e32 v196, s19, v226
	v_mad_i64_i32 v[230:231], s[14:15], v196, s90, v[204:205]
	global_load_dwordx4 v[122:125], v[230:231], off
	s_cmp_lg_u64 s[40:41], 0
	s_cbranch_scc0 .Lmf_nok1_1
	v_add_u32_e32 v196, s19, v227
	v_mad_i64_i32 v[230:231], s[14:15], v196, s90, v[206:207]
.Lmf_nok1_1:
	global_load_dwordx4 v[126:129], v[230:231], off
	s_add_i32 s12, s19, 0xffffff00
	s_ashr_i32 s13, s12, 31
	v_lshl_add_u64 v[230:231], s[12:13], 1, v[200:201]
	global_load_dwordx4 v[138:141], v[230:231], off offset:384
	v_exp_f32_e32 v34, v34
	v_exp_f32_e32 v35, v35
	v_exp_f32_e32 v36, v36
	v_exp_f32_e32 v37, v37
	s_waitcnt lgkmcnt(3)
	v_mfma_f32_32x32x16_bf16 v[66:81], v[162:165], v[98:101], v[146:161]
	ds_read_b128 v[180:183], v216 offset:64
	v_add_f32_e32 v171, v34, v171
	v_exp_f32_e32 v38, v38
	v_exp_f32_e32 v39, v39
	s_waitcnt lgkmcnt(3)
	v_mfma_f32_32x32x16_bf16 v[82:97], v[166:169], v[98:101], v[146:161]
	ds_read_b128 v[184:187], v216 offset:6720
	v_add_f32_e32 v171, v36, v171
	v_exp_f32_e32 v40, v40
	v_add_f32_e32 v197, v35, v37
	v_exp_f32_e32 v41, v41
	s_waitcnt lgkmcnt(3)
	v_mfma_f32_32x32x16_bf16 v[66:81], v[172:175], v[102:105], v[66:81]
	ds_read_b128 v[188:191], v216 offset:96
	v_add_f32_e32 v171, v38, v171
	v_add_f32_e32 v197, v39, v197
	v_cvt_pk_bf16_f32 v34, v34, v35
	v_add_f32_e32 v171, v40, v171
	v_cvt_pk_bf16_f32 v35, v36, v37
	v_add_f32_e32 v197, v41, v197
	v_cvt_pk_bf16_f32 v36, v38, v39
	s_waitcnt lgkmcnt(3)
	v_mfma_f32_32x32x16_bf16 v[82:97], v[176:179], v[102:105], v[82:97]
	ds_read_b128 v[192:195], v216 offset:6752
	v_cvt_pk_bf16_f32 v37, v40, v41
	v_exp_f32_e32 v42, v42
	v_exp_f32_e32 v43, v43
	v_exp_f32_e32 v44, v44
	s_waitcnt lgkmcnt(3)
	v_mfma_f32_32x32x16_bf16 v[66:81], v[180:183], v[106:109], v[66:81]
	ds_read_b128 v[162:165], v216 offset:128
	v_exp_f32_e32 v45, v45
	v_add_f32_e32 v171, v42, v171
	v_exp_f32_e32 v46, v46
	s_waitcnt lgkmcnt(3)
	v_mfma_f32_32x32x16_bf16 v[82:97], v[184:187], v[106:109], v[82:97]
	ds_read_b128 v[166:169], v216 offset:6784
	v_add_f32_e32 v197, v43, v197
	v_exp_f32_e32 v47, v47
	v_add_f32_e32 v171, v44, v171
	v_exp_f32_e32 v48, v48
	s_waitcnt lgkmcnt(3)
	v_mfma_f32_32x32x16_bf16 v[66:81], v[188:191], v[110:113], v[66:81]
	ds_read_b128 v[172:175], v216 offset:160
	v_add_f32_e32 v197, v45, v197
	v_exp_f32_e32 v49, v49
	v_add_f32_e32 v171, v46, v171
	v_add_f32_e32 v197, v47, v197
	v_cvt_pk_bf16_f32 v42, v42, v43
	v_add_f32_e32 v171, v48, v171
	s_waitcnt lgkmcnt(3)
	v_mfma_f32_32x32x16_bf16 v[82:97], v[192:195], v[110:113], v[82:97]
	ds_read_b128 v[176:179], v216 offset:6816
	v_cvt_pk_bf16_f32 v43, v44, v45
	v_add_f32_e32 v197, v49, v197
	v_cvt_pk_bf16_f32 v44, v46, v47
	v_cvt_pk_bf16_f32 v45, v48, v49
	v_exp_f32_e32 v50, v50
	s_waitcnt lgkmcnt(3)
	v_mfma_f32_32x32x16_bf16 v[66:81], v[162:165], v[114:117], v[66:81]
	ds_read_b128 v[180:183], v217 offset:35840
	v_exp_f32_e32 v51, v51
	v_exp_f32_e32 v52, v52
	v_exp_f32_e32 v53, v53
	s_waitcnt lgkmcnt(3)
	v_mfma_f32_32x32x16_bf16 v[82:97], v[166:169], v[114:117], v[82:97]
	ds_read_b128 v[184:187], v217 offset:40448
	v_add_f32_e32 v171, v50, v171
	v_exp_f32_e32 v54, v54
	v_add_f32_e32 v197, v51, v197
	v_exp_f32_e32 v55, v55
	s_waitcnt lgkmcnt(3)
	v_mfma_f32_32x32x16_bf16 v[66:81], v[172:175], v[118:121], v[66:81]
	ds_read_b128 v[188:191], v217 offset:35872
	v_add_f32_e32 v171, v52, v171
	v_exp_f32_e32 v56, v56
	v_add_f32_e32 v197, v53, v197
	v_exp_f32_e32 v57, v57
	v_add_f32_e32 v171, v54, v171
	s_waitcnt lgkmcnt(3)
	v_mfma_f32_32x32x16_bf16 v[82:97], v[176:179], v[118:121], v[82:97]
	ds_read_b128 v[192:195], v217 offset:40480
	v_add_f32_e32 v197, v55, v197
	v_cvt_pk_bf16_f32 v50, v50, v51
	v_add_f32_e32 v171, v56, v171
	v_cvt_pk_bf16_f32 v51, v52, v53
	v_add_f32_e32 v197, v57, v197
	v_cvt_pk_bf16_f32 v52, v54, v55
	s_waitcnt lgkmcnt(3)
	v_mfma_f32_32x32x16_bf16 v[18:33], v[180:183], v[34:37], v[18:33]
	ds_read_b128 v[162:165], v217 offset:35904
	v_cvt_pk_bf16_f32 v53, v56, v57
	v_exp_f32_e32 v58, v58
	v_exp_f32_e32 v59, v59
	v_exp_f32_e32 v60, v60
	s_waitcnt lgkmcnt(3)
	v_mfma_f32_32x32x16_bf16 v[2:17], v[184:187], v[34:37], v[2:17]
	ds_read_b128 v[166:169], v217 offset:40512
	v_exp_f32_e32 v61, v61
	v_add_f32_e32 v171, v58, v171
	v_exp_f32_e32 v62, v62
	s_waitcnt lgkmcnt(3)
	v_mfma_f32_32x32x16_bf16 v[18:33], v[188:191], v[42:45], v[18:33]
	ds_read_b128 v[172:175], v217 offset:35936
	v_add_f32_e32 v197, v59, v197
	v_exp_f32_e32 v63, v63
	v_add_f32_e32 v171, v60, v171
	v_exp_f32_e32 v64, v64
	v_add_f32_e32 v197, v61, v197
	s_waitcnt lgkmcnt(3)
	v_mfma_f32_32x32x16_bf16 v[2:17], v[192:195], v[42:45], v[2:17]
	ds_read_b128 v[176:179], v217 offset:40544
	s_waitcnt vmcnt(3)
	ds_write_b128 v228, v[130:133] offset:13312
	ds_write_b128 v238, v[134:137] offset:13312
	ds_write2_b64 v225, v[142:143], v[144:145] offset1:2
	v_exp_f32_e32 v65, v65
	v_add_f32_e32 v171, v62, v171
	v_add_f32_e32 v197, v63, v197
	v_cvt_pk_bf16_f32 v58, v58, v59
	v_add_f32_e32 v171, v64, v171
	s_waitcnt lgkmcnt(6)
	v_mfma_f32_32x32x16_bf16 v[18:33], v[162:165], v[50:53], v[18:33]
	v_cvt_pk_bf16_f32 v59, v60, v61
	v_add_f32_e32 v197, v65, v197
	v_cvt_pk_bf16_f32 v60, v62, v63
	v_cvt_pk_bf16_f32 v61, v64, v65
	v_max3_f32 v1, v66, v67, v68
	v_max3_f32 v170, v69, v70, v71
	s_waitcnt lgkmcnt(5)
	v_mfma_f32_32x32x16_bf16 v[2:17], v[166:169], v[50:53], v[2:17]
	v_max3_f32 v1, v1, v72, v73
	v_max3_f32 v170, v170, v74, v75
	v_max3_f32 v1, v1, v76, v77
	v_max3_f32 v170, v170, v78, v79
	v_max3_f32 v1, v1, v80, v81
	v_max3_f32 v170, v170, v82, v83
	s_waitcnt lgkmcnt(4)
	v_mfma_f32_32x32x16_bf16 v[18:33], v[172:175], v[58:61], v[18:33]
	v_max3_f32 v1, v1, v84, v85
	v_max3_f32 v170, v170, v86, v87
	v_max3_f32 v1, v1, v88, v89
	v_max3_f32 v170, v170, v90, v91
	v_max3_f32 v1, v1, v92, v93
	v_max3_f32 v170, v170, v94, v95
	v_max3_f32 v1, v1, v96, v97
	s_waitcnt lgkmcnt(3)
	v_mfma_f32_32x32x16_bf16 v[2:17], v[176:179], v[58:61], v[2:17]
	v_max_f32_e32 v1, v1, v170
	v_mov_b32_e32 v170, v1
	v_add_f32_e32 v171, v197, v171
	s_nop 0
	v_permlane32_swap_b32_e32 v1, v170
	v_max_f32_e32 v1, v1, v170
	v_cmp_lt_f32_e32 vcc, s93, v1
	s_cbranch_vccnz .Lmf_slow_1
